# rstd_table: residual-row sum-of-squares partials loaded as full 128-B lines (8 rows per instruction) with an 8-lane DPP reduction instead of 64 scattered lines per instruction; plus epilogue load tran
# baseline (speedup 1.0000x reference)
; #define GAS __attribute__((address_space(1)))
; #define SB() __builtin_amdgcn_sched_barrier(0)
; DI const LAS float* rstd_table(const Frame& F) {
;     ...
;     for (int r = F.tid; r < 2048; r += 512) { f32x4 p[8];
; #pragma unroll
;         for (int q = 0; q < 8; ++q) p[q] = ((const GAS f32x4*)(P + (size_t)r * 32))[q];
;         SB();
;         f32x4 t = (p[0] + p[1]) + (p[2] + p[3]) + ((p[4] + p[5]) + (p[6] + p[7]));
;         tab[r] = 1.f / sqrtf(((t[0] + t[1]) + (t[2] + t[3])) * (1.f / D) + NORM_EPS);
.LBB0_366:
	v_mbcnt_lo_u32_b32 v139, -1, 0
	v_mbcnt_hi_u32_b32 v139, -1, v139
	v_and_b32_e32 v138, 7, v139
	v_mul_u32_u24_e32 v140, 0x70, v138
	v_sub_co_u32_e32 v0, vcc, v0, v140
	s_nop 1
	v_subbrev_co_u32_e32 v1, vcc, 0, v1, vcc
	v_lshl_add_u64 v[132:133], v[0:1], 0, s[16:17]
	v_lshl_add_u64 v[134:135], v[132:133], 0, s[16:17]
	v_lshl_add_u64 v[136:137], v[134:135], 0, s[16:17]
	global_load_dwordx4 v[4:7], v[0:1], off
	global_load_dwordx4 v[8:11], v[0:1], off offset:128
	global_load_dwordx4 v[12:15], v[0:1], off offset:256
	global_load_dwordx4 v[16:19], v[0:1], off offset:384
	global_load_dwordx4 v[20:23], v[0:1], off offset:512
	global_load_dwordx4 v[24:27], v[0:1], off offset:640
	global_load_dwordx4 v[28:31], v[0:1], off offset:768
	global_load_dwordx4 v[32:35], v[0:1], off offset:896
	global_load_dwordx4 v[36:39], v[132:133], off
	global_load_dwordx4 v[40:43], v[132:133], off offset:128
	global_load_dwordx4 v[44:47], v[132:133], off offset:256
	global_load_dwordx4 v[48:51], v[132:133], off offset:384
	global_load_dwordx4 v[52:55], v[132:133], off offset:512
	global_load_dwordx4 v[56:59], v[132:133], off offset:640
	global_load_dwordx4 v[60:63], v[132:133], off offset:768
	global_load_dwordx4 v[64:67], v[132:133], off offset:896
	global_load_dwordx4 v[68:71], v[134:135], off
	global_load_dwordx4 v[72:75], v[134:135], off offset:128
	global_load_dwordx4 v[76:79], v[134:135], off offset:256
	global_load_dwordx4 v[80:83], v[134:135], off offset:384
	global_load_dwordx4 v[84:87], v[134:135], off offset:512
	global_load_dwordx4 v[88:91], v[134:135], off offset:640
	global_load_dwordx4 v[92:95], v[134:135], off offset:768
	global_load_dwordx4 v[96:99], v[134:135], off offset:896
	global_load_dwordx4 v[100:103], v[136:137], off
	global_load_dwordx4 v[104:107], v[136:137], off offset:128
	global_load_dwordx4 v[108:111], v[136:137], off offset:256
	global_load_dwordx4 v[112:115], v[136:137], off offset:384
	global_load_dwordx4 v[116:119], v[136:137], off offset:512
	global_load_dwordx4 v[120:123], v[136:137], off offset:640
	global_load_dwordx4 v[124:127], v[136:137], off offset:768
	global_load_dwordx4 v[128:131], v[136:137], off offset:896
	s_waitcnt vmcnt(24)
	v_pk_add_f32 v[4:5], v[4:5], v[6:7]
	v_pk_add_f32 v[8:9], v[8:9], v[10:11]
	v_pk_add_f32 v[12:13], v[12:13], v[14:15]
	v_pk_add_f32 v[16:17], v[16:17], v[18:19]
	v_pk_add_f32 v[20:21], v[20:21], v[22:23]
	v_pk_add_f32 v[24:25], v[24:25], v[26:27]
	v_pk_add_f32 v[28:29], v[28:29], v[30:31]
	v_pk_add_f32 v[32:33], v[32:33], v[34:35]
	v_add_f32_e32 v4, v4, v5
	v_add_f32_e32 v8, v8, v9
	v_add_f32_e32 v12, v12, v13
	v_add_f32_e32 v16, v16, v17
	v_add_f32_e32 v20, v20, v21
	v_add_f32_e32 v24, v24, v25
	v_add_f32_e32 v28, v28, v29
	v_add_f32_e32 v32, v32, v33
	v_add_f32_dpp v4, v4, v4 quad_perm:[1,0,3,2] row_mask:0xf bank_mask:0xf
	v_add_f32_dpp v8, v8, v8 quad_perm:[1,0,3,2] row_mask:0xf bank_mask:0xf
	v_add_f32_dpp v12, v12, v12 quad_perm:[1,0,3,2] row_mask:0xf bank_mask:0xf
	v_add_f32_dpp v16, v16, v16 quad_perm:[1,0,3,2] row_mask:0xf bank_mask:0xf
	v_add_f32_dpp v20, v20, v20 quad_perm:[1,0,3,2] row_mask:0xf bank_mask:0xf
	v_add_f32_dpp v24, v24, v24 quad_perm:[1,0,3,2] row_mask:0xf bank_mask:0xf
	v_add_f32_dpp v28, v28, v28 quad_perm:[1,0,3,2] row_mask:0xf bank_mask:0xf
	v_add_f32_dpp v32, v32, v32 quad_perm:[1,0,3,2] row_mask:0xf bank_mask:0xf
	v_add_f32_dpp v4, v4, v4 quad_perm:[2,3,0,1] row_mask:0xf bank_mask:0xf
	v_add_f32_dpp v8, v8, v8 quad_perm:[2,3,0,1] row_mask:0xf bank_mask:0xf
	v_add_f32_dpp v12, v12, v12 quad_perm:[2,3,0,1] row_mask:0xf bank_mask:0xf
	v_add_f32_dpp v16, v16, v16 quad_perm:[2,3,0,1] row_mask:0xf bank_mask:0xf
	v_add_f32_dpp v20, v20, v20 quad_perm:[2,3,0,1] row_mask:0xf bank_mask:0xf
	v_add_f32_dpp v24, v24, v24 quad_perm:[2,3,0,1] row_mask:0xf bank_mask:0xf
	v_add_f32_dpp v28, v28, v28 quad_perm:[2,3,0,1] row_mask:0xf bank_mask:0xf
	v_add_f32_dpp v32, v32, v32 quad_perm:[2,3,0,1] row_mask:0xf bank_mask:0xf
	v_add_f32_dpp v4, v4, v4 row_half_mirror row_mask:0xf bank_mask:0xf
	v_add_f32_dpp v8, v8, v8 row_half_mirror row_mask:0xf bank_mask:0xf
	v_add_f32_dpp v12, v12, v12 row_half_mirror row_mask:0xf bank_mask:0xf
	v_add_f32_dpp v16, v16, v16 row_half_mirror row_mask:0xf bank_mask:0xf
	v_add_f32_dpp v20, v20, v20 row_half_mirror row_mask:0xf bank_mask:0xf
	v_add_f32_dpp v24, v24, v24 row_half_mirror row_mask:0xf bank_mask:0xf
	v_add_f32_dpp v28, v28, v28 row_half_mirror row_mask:0xf bank_mask:0xf
	v_add_f32_dpp v32, v32, v32 row_half_mirror row_mask:0xf bank_mask:0xf
	v_cmp_eq_u32_e32 vcc, 1, v138
	s_nop 1
	v_cndmask_b32_e32 v4, v4, v8, vcc
	v_cmp_eq_u32_e32 vcc, 2, v138
	s_nop 1
	v_cndmask_b32_e32 v4, v4, v12, vcc
	v_cmp_eq_u32_e32 vcc, 3, v138
	s_nop 1
	v_cndmask_b32_e32 v4, v4, v16, vcc
	v_cmp_eq_u32_e32 vcc, 4, v138
	s_nop 1
	v_cndmask_b32_e32 v4, v4, v20, vcc
	v_cmp_eq_u32_e32 vcc, 5, v138
	s_nop 1
	v_cndmask_b32_e32 v4, v4, v24, vcc
	v_cmp_eq_u32_e32 vcc, 6, v138
	s_nop 1
	v_cndmask_b32_e32 v4, v4, v28, vcc
	v_cmp_eq_u32_e32 vcc, 7, v138
	s_nop 1
	v_cndmask_b32_e32 v4, v4, v32, vcc
	s_waitcnt vmcnt(16)
; #define GAS __attribute__((address_space(1)))
; #define SB() __builtin_amdgcn_sched_barrier(0)
; DI const LAS float* rstd_table(const Frame& F) {
;     ...
;     for (int r = F.tid; r < 2048; r += 512) { f32x4 p[8];
; #pragma unroll
;         for (int q = 0; q < 8; ++q) p[q] = ((const GAS f32x4*)(P + (size_t)r * 32))[q];
;         SB();
;         f32x4 t = (p[0] + p[1]) + (p[2] + p[3]) + ((p[4] + p[5]) + (p[6] + p[7]));
;         tab[r] = 1.f / sqrtf(((t[0] + t[1]) + (t[2] + t[3])) * (1.f / D) + NORM_EPS);
	v_pk_add_f32 v[36:37], v[36:37], v[38:39]
	v_pk_add_f32 v[40:41], v[40:41], v[42:43]
	v_pk_add_f32 v[44:45], v[44:45], v[46:47]
	v_pk_add_f32 v[48:49], v[48:49], v[50:51]
	v_pk_add_f32 v[52:53], v[52:53], v[54:55]
	v_pk_add_f32 v[56:57], v[56:57], v[58:59]
	v_pk_add_f32 v[60:61], v[60:61], v[62:63]
	v_pk_add_f32 v[64:65], v[64:65], v[66:67]
	v_add_f32_e32 v36, v36, v37
	v_add_f32_e32 v40, v40, v41
	v_add_f32_e32 v44, v44, v45
	v_add_f32_e32 v48, v48, v49
	v_add_f32_e32 v52, v52, v53
	v_add_f32_e32 v56, v56, v57
	v_add_f32_e32 v60, v60, v61
	v_add_f32_e32 v64, v64, v65
	v_add_f32_dpp v36, v36, v36 quad_perm:[1,0,3,2] row_mask:0xf bank_mask:0xf
	v_add_f32_dpp v40, v40, v40 quad_perm:[1,0,3,2] row_mask:0xf bank_mask:0xf
	v_add_f32_dpp v44, v44, v44 quad_perm:[1,0,3,2] row_mask:0xf bank_mask:0xf
	v_add_f32_dpp v48, v48, v48 quad_perm:[1,0,3,2] row_mask:0xf bank_mask:0xf
	v_add_f32_dpp v52, v52, v52 quad_perm:[1,0,3,2] row_mask:0xf bank_mask:0xf
	v_add_f32_dpp v56, v56, v56 quad_perm:[1,0,3,2] row_mask:0xf bank_mask:0xf
	v_add_f32_dpp v60, v60, v60 quad_perm:[1,0,3,2] row_mask:0xf bank_mask:0xf
	v_add_f32_dpp v64, v64, v64 quad_perm:[1,0,3,2] row_mask:0xf bank_mask:0xf
	v_add_f32_dpp v36, v36, v36 quad_perm:[2,3,0,1] row_mask:0xf bank_mask:0xf
	v_add_f32_dpp v40, v40, v40 quad_perm:[2,3,0,1] row_mask:0xf bank_mask:0xf
	v_add_f32_dpp v44, v44, v44 quad_perm:[2,3,0,1] row_mask:0xf bank_mask:0xf
	v_add_f32_dpp v48, v48, v48 quad_perm:[2,3,0,1] row_mask:0xf bank_mask:0xf
	v_add_f32_dpp v52, v52, v52 quad_perm:[2,3,0,1] row_mask:0xf bank_mask:0xf
	v_add_f32_dpp v56, v56, v56 quad_perm:[2,3,0,1] row_mask:0xf bank_mask:0xf
	v_add_f32_dpp v60, v60, v60 quad_perm:[2,3,0,1] row_mask:0xf bank_mask:0xf
	v_add_f32_dpp v64, v64, v64 quad_perm:[2,3,0,1] row_mask:0xf bank_mask:0xf
	v_add_f32_dpp v36, v36, v36 row_half_mirror row_mask:0xf bank_mask:0xf
	v_add_f32_dpp v40, v40, v40 row_half_mirror row_mask:0xf bank_mask:0xf
	v_add_f32_dpp v44, v44, v44 row_half_mirror row_mask:0xf bank_mask:0xf
	v_add_f32_dpp v48, v48, v48 row_half_mirror row_mask:0xf bank_mask:0xf
	v_add_f32_dpp v52, v52, v52 row_half_mirror row_mask:0xf bank_mask:0xf
	v_add_f32_dpp v56, v56, v56 row_half_mirror row_mask:0xf bank_mask:0xf
	v_add_f32_dpp v60, v60, v60 row_half_mirror row_mask:0xf bank_mask:0xf
	v_add_f32_dpp v64, v64, v64 row_half_mirror row_mask:0xf bank_mask:0xf
	v_cmp_eq_u32_e32 vcc, 1, v138
	s_nop 1
	v_cndmask_b32_e32 v36, v36, v40, vcc
	v_cmp_eq_u32_e32 vcc, 2, v138
	s_nop 1
	v_cndmask_b32_e32 v36, v36, v44, vcc
	v_cmp_eq_u32_e32 vcc, 3, v138
	s_nop 1
	v_cndmask_b32_e32 v36, v36, v48, vcc
	v_cmp_eq_u32_e32 vcc, 4, v138
	s_nop 1
	v_cndmask_b32_e32 v36, v36, v52, vcc
	v_cmp_eq_u32_e32 vcc, 5, v138
	s_nop 1
	v_cndmask_b32_e32 v36, v36, v56, vcc
	v_cmp_eq_u32_e32 vcc, 6, v138
	s_nop 1
	v_cndmask_b32_e32 v36, v36, v60, vcc
	v_cmp_eq_u32_e32 vcc, 7, v138
	s_nop 1
	v_cndmask_b32_e32 v36, v36, v64, vcc
	s_waitcnt vmcnt(8)
	v_pk_add_f32 v[68:69], v[68:69], v[70:71]
	v_pk_add_f32 v[72:73], v[72:73], v[74:75]
	v_pk_add_f32 v[76:77], v[76:77], v[78:79]
	v_pk_add_f32 v[80:81], v[80:81], v[82:83]
	v_pk_add_f32 v[84:85], v[84:85], v[86:87]
	v_pk_add_f32 v[88:89], v[88:89], v[90:91]
	v_pk_add_f32 v[92:93], v[92:93], v[94:95]
	v_pk_add_f32 v[96:97], v[96:97], v[98:99]
	v_add_f32_e32 v68, v68, v69
	v_add_f32_e32 v72, v72, v73
	v_add_f32_e32 v76, v76, v77
	v_add_f32_e32 v80, v80, v81
	v_add_f32_e32 v84, v84, v85
	v_add_f32_e32 v88, v88, v89
	v_add_f32_e32 v92, v92, v93
	v_add_f32_e32 v96, v96, v97
	v_add_f32_dpp v68, v68, v68 quad_perm:[1,0,3,2] row_mask:0xf bank_mask:0xf
	v_add_f32_dpp v72, v72, v72 quad_perm:[1,0,3,2] row_mask:0xf bank_mask:0xf
	v_add_f32_dpp v76, v76, v76 quad_perm:[1,0,3,2] row_mask:0xf bank_mask:0xf
	v_add_f32_dpp v80, v80, v80 quad_perm:[1,0,3,2] row_mask:0xf bank_mask:0xf
	v_add_f32_dpp v84, v84, v84 quad_perm:[1,0,3,2] row_mask:0xf bank_mask:0xf
	v_add_f32_dpp v88, v88, v88 quad_perm:[1,0,3,2] row_mask:0xf bank_mask:0xf
	v_add_f32_dpp v92, v92, v92 quad_perm:[1,0,3,2] row_mask:0xf bank_mask:0xf
	v_add_f32_dpp v96, v96, v96 quad_perm:[1,0,3,2] row_mask:0xf bank_mask:0xf
	v_add_f32_dpp v68, v68, v68 quad_perm:[2,3,0,1] row_mask:0xf bank_mask:0xf
	v_add_f32_dpp v72, v72, v72 quad_perm:[2,3,0,1] row_mask:0xf bank_mask:0xf
	v_add_f32_dpp v76, v76, v76 quad_perm:[2,3,0,1] row_mask:0xf bank_mask:0xf
	v_add_f32_dpp v80, v80, v80 quad_perm:[2,3,0,1] row_mask:0xf bank_mask:0xf
	v_add_f32_dpp v84, v84, v84 quad_perm:[2,3,0,1] row_mask:0xf bank_mask:0xf
	v_add_f32_dpp v88, v88, v88 quad_perm:[2,3,0,1] row_mask:0xf bank_mask:0xf
	v_add_f32_dpp v92, v92, v92 quad_perm:[2,3,0,1] row_mask:0xf bank_mask:0xf
	v_add_f32_dpp v96, v96, v96 quad_perm:[2,3,0,1] row_mask:0xf bank_mask:0xf
	v_add_f32_dpp v68, v68, v68 row_half_mirror row_mask:0xf bank_mask:0xf
	v_add_f32_dpp v72, v72, v72 row_half_mirror row_mask:0xf bank_mask:0xf
	v_add_f32_dpp v76, v76, v76 row_half_mirror row_mask:0xf bank_mask:0xf
	v_add_f32_dpp v80, v80, v80 row_half_mirror row_mask:0xf bank_mask:0xf
	v_add_f32_dpp v84, v84, v84 row_half_mirror row_mask:0xf bank_mask:0xf
	v_add_f32_dpp v88, v88, v88 row_half_mirror row_mask:0xf bank_mask:0xf
	v_add_f32_dpp v92, v92, v92 row_half_mirror row_mask:0xf bank_mask:0xf
	v_add_f32_dpp v96, v96, v96 row_half_mirror row_mask:0xf bank_mask:0xf
	v_cmp_eq_u32_e32 vcc, 1, v138
	s_nop 1
	v_cndmask_b32_e32 v68, v68, v72, vcc
	v_cmp_eq_u32_e32 vcc, 2, v138
	s_nop 1
	v_cndmask_b32_e32 v68, v68, v76, vcc
	v_cmp_eq_u32_e32 vcc, 3, v138
	s_nop 1
	v_cndmask_b32_e32 v68, v68, v80, vcc
	v_cmp_eq_u32_e32 vcc, 4, v138
	s_nop 1
	v_cndmask_b32_e32 v68, v68, v84, vcc
	v_cmp_eq_u32_e32 vcc, 5, v138
	s_nop 1
	v_cndmask_b32_e32 v68, v68, v88, vcc
	v_cmp_eq_u32_e32 vcc, 6, v138
	s_nop 1
	v_cndmask_b32_e32 v68, v68, v92, vcc
	v_cmp_eq_u32_e32 vcc, 7, v138
	s_nop 1
	v_cndmask_b32_e32 v68, v68, v96, vcc
	s_waitcnt vmcnt(0)
; #define GAS __attribute__((address_space(1)))
; #define SB() __builtin_amdgcn_sched_barrier(0)
; DI const LAS float* rstd_table(const Frame& F) {
;     ...
;     for (int r = F.tid; r < 2048; r += 512) { f32x4 p[8];
; #pragma unroll
;         for (int q = 0; q < 8; ++q) p[q] = ((const GAS f32x4*)(P + (size_t)r * 32))[q];
;         SB();
;         f32x4 t = (p[0] + p[1]) + (p[2] + p[3]) + ((p[4] + p[5]) + (p[6] + p[7]));
;         tab[r] = 1.f / sqrtf(((t[0] + t[1]) + (t[2] + t[3])) * (1.f / D) + NORM_EPS);
	v_pk_add_f32 v[100:101], v[100:101], v[102:103]
	v_pk_add_f32 v[104:105], v[104:105], v[106:107]
	v_pk_add_f32 v[108:109], v[108:109], v[110:111]
	v_pk_add_f32 v[112:113], v[112:113], v[114:115]
	v_pk_add_f32 v[116:117], v[116:117], v[118:119]
	v_pk_add_f32 v[120:121], v[120:121], v[122:123]
	v_pk_add_f32 v[124:125], v[124:125], v[126:127]
	v_pk_add_f32 v[128:129], v[128:129], v[130:131]
	v_add_f32_e32 v100, v100, v101
	v_add_f32_e32 v104, v104, v105
	v_add_f32_e32 v108, v108, v109
	v_add_f32_e32 v112, v112, v113
	v_add_f32_e32 v116, v116, v117
	v_add_f32_e32 v120, v120, v121
	v_add_f32_e32 v124, v124, v125
	v_add_f32_e32 v128, v128, v129
	v_add_f32_dpp v100, v100, v100 quad_perm:[1,0,3,2] row_mask:0xf bank_mask:0xf
	v_add_f32_dpp v104, v104, v104 quad_perm:[1,0,3,2] row_mask:0xf bank_mask:0xf
	v_add_f32_dpp v108, v108, v108 quad_perm:[1,0,3,2] row_mask:0xf bank_mask:0xf
	v_add_f32_dpp v112, v112, v112 quad_perm:[1,0,3,2] row_mask:0xf bank_mask:0xf
	v_add_f32_dpp v116, v116, v116 quad_perm:[1,0,3,2] row_mask:0xf bank_mask:0xf
	v_add_f32_dpp v120, v120, v120 quad_perm:[1,0,3,2] row_mask:0xf bank_mask:0xf
	v_add_f32_dpp v124, v124, v124 quad_perm:[1,0,3,2] row_mask:0xf bank_mask:0xf
	v_add_f32_dpp v128, v128, v128 quad_perm:[1,0,3,2] row_mask:0xf bank_mask:0xf
	v_add_f32_dpp v100, v100, v100 quad_perm:[2,3,0,1] row_mask:0xf bank_mask:0xf
	v_add_f32_dpp v104, v104, v104 quad_perm:[2,3,0,1] row_mask:0xf bank_mask:0xf
	v_add_f32_dpp v108, v108, v108 quad_perm:[2,3,0,1] row_mask:0xf bank_mask:0xf
	v_add_f32_dpp v112, v112, v112 quad_perm:[2,3,0,1] row_mask:0xf bank_mask:0xf
	v_add_f32_dpp v116, v116, v116 quad_perm:[2,3,0,1] row_mask:0xf bank_mask:0xf
	v_add_f32_dpp v120, v120, v120 quad_perm:[2,3,0,1] row_mask:0xf bank_mask:0xf
	v_add_f32_dpp v124, v124, v124 quad_perm:[2,3,0,1] row_mask:0xf bank_mask:0xf
	v_add_f32_dpp v128, v128, v128 quad_perm:[2,3,0,1] row_mask:0xf bank_mask:0xf
	v_add_f32_dpp v100, v100, v100 row_half_mirror row_mask:0xf bank_mask:0xf
	v_add_f32_dpp v104, v104, v104 row_half_mirror row_mask:0xf bank_mask:0xf
	v_add_f32_dpp v108, v108, v108 row_half_mirror row_mask:0xf bank_mask:0xf
	v_add_f32_dpp v112, v112, v112 row_half_mirror row_mask:0xf bank_mask:0xf
	v_add_f32_dpp v116, v116, v116 row_half_mirror row_mask:0xf bank_mask:0xf
	v_add_f32_dpp v120, v120, v120 row_half_mirror row_mask:0xf bank_mask:0xf
	v_add_f32_dpp v124, v124, v124 row_half_mirror row_mask:0xf bank_mask:0xf
	v_add_f32_dpp v128, v128, v128 row_half_mirror row_mask:0xf bank_mask:0xf
	v_cmp_eq_u32_e32 vcc, 1, v138
	s_nop 1
	v_cndmask_b32_e32 v100, v100, v104, vcc
	v_cmp_eq_u32_e32 vcc, 2, v138
	s_nop 1
	v_cndmask_b32_e32 v100, v100, v108, vcc
	v_cmp_eq_u32_e32 vcc, 3, v138
	s_nop 1
	v_cndmask_b32_e32 v100, v100, v112, vcc
	v_cmp_eq_u32_e32 vcc, 4, v138
	s_nop 1
	v_cndmask_b32_e32 v100, v100, v116, vcc
	v_cmp_eq_u32_e32 vcc, 5, v138
	s_nop 1
	v_cndmask_b32_e32 v100, v100, v120, vcc
	v_cmp_eq_u32_e32 vcc, 6, v138
	s_nop 1
	v_cndmask_b32_e32 v100, v100, v124, vcc
	v_cmp_eq_u32_e32 vcc, 7, v138
	s_nop 1
	v_cndmask_b32_e32 v100, v100, v128, vcc
	v_fmamk_f32 v4, v4, 0x3a000000, v225
	v_mul_f32_e32 v5, 0x4f800000, v4
	v_cmp_gt_f32_e32 vcc, s14, v4
	s_nop 1
	v_cndmask_b32_e32 v4, v4, v5, vcc
	v_sqrt_f32_e32 v5, v4
	s_nop 0
	v_add_u32_e32 v6, -1, v5
	v_fma_f32 v7, -v6, v5, v4
	v_cmp_ge_f32_e64 s[4:5], 0, v7
	v_add_u32_e32 v7, 1, v5
	s_nop 0
	v_cndmask_b32_e64 v6, v5, v6, s[4:5]
	v_fma_f32 v5, -v7, v5, v4
	v_cmp_lt_f32_e64 s[4:5], 0, v5
	s_nop 1
	v_cndmask_b32_e64 v5, v6, v7, s[4:5]
	v_mul_f32_e32 v6, 0x37800000, v5
	v_cndmask_b32_e32 v5, v5, v6, vcc
	v_cmp_class_f32_e32 vcc, v4, v226
	s_nop 1
	v_cndmask_b32_e32 v4, v5, v4, vcc
	v_div_scale_f32 v5, s[0:1], v4, v4, 1.0
	v_rcp_f32_e32 v6, v5
	s_nop 0
	v_fma_f32 v7, -v5, v6, 1.0
	v_fmac_f32_e32 v6, v7, v6
	v_div_scale_f32 v7, vcc, 1.0, v4, 1.0
	v_mul_f32_e32 v8, v7, v6
	v_fma_f32 v9, -v5, v8, v7
	v_fmac_f32_e32 v8, v9, v6
	v_fma_f32 v5, -v5, v8, v7
	v_div_fmas_f32 v5, v5, v6, v8
	v_div_fixup_f32 v4, v5, v4, 1.0
	ds_write_b32 v3, v4
	v_mov_b32_e32 v4, v36
	v_fmamk_f32 v4, v4, 0x3a000000, v225
	v_mul_f32_e32 v5, 0x4f800000, v4
	v_cmp_gt_f32_e32 vcc, s14, v4
	s_nop 1
	v_cndmask_b32_e32 v4, v4, v5, vcc
	v_sqrt_f32_e32 v5, v4
	s_nop 0
	v_add_u32_e32 v6, -1, v5
	v_fma_f32 v7, -v6, v5, v4
	v_cmp_ge_f32_e64 s[4:5], 0, v7
	v_add_u32_e32 v7, 1, v5
	s_nop 0
	v_cndmask_b32_e64 v6, v5, v6, s[4:5]
	v_fma_f32 v5, -v7, v5, v4
	v_cmp_lt_f32_e64 s[4:5], 0, v5
	s_nop 1
	v_cndmask_b32_e64 v5, v6, v7, s[4:5]
	v_mul_f32_e32 v6, 0x37800000, v5
	v_cndmask_b32_e32 v5, v5, v6, vcc
	v_cmp_class_f32_e32 vcc, v4, v226
	s_nop 1
	v_cndmask_b32_e32 v4, v5, v4, vcc
	v_div_scale_f32 v5, s[0:1], v4, v4, 1.0
	v_rcp_f32_e32 v6, v5
	s_nop 0
	v_fma_f32 v7, -v5, v6, 1.0
	v_fmac_f32_e32 v6, v7, v6
	v_div_scale_f32 v7, vcc, 1.0, v4, 1.0
	v_mul_f32_e32 v8, v7, v6
	v_fma_f32 v9, -v5, v8, v7
	v_fmac_f32_e32 v8, v9, v6
	v_fma_f32 v5, -v5, v8, v7
	v_div_fmas_f32 v5, v5, v6, v8
	v_div_fixup_f32 v4, v5, v4, 1.0
	ds_write_b32 v3, v4 offset:2048
	v_mov_b32_e32 v4, v68
	v_fmamk_f32 v4, v4, 0x3a000000, v225
	v_mul_f32_e32 v5, 0x4f800000, v4
	v_cmp_gt_f32_e32 vcc, s14, v4
	s_nop 1
	v_cndmask_b32_e32 v4, v4, v5, vcc
	v_sqrt_f32_e32 v5, v4
	s_nop 0
	v_add_u32_e32 v6, -1, v5
	v_fma_f32 v7, -v6, v5, v4
	v_cmp_ge_f32_e64 s[4:5], 0, v7
	v_add_u32_e32 v7, 1, v5
	s_nop 0
	v_cndmask_b32_e64 v6, v5, v6, s[4:5]
	v_fma_f32 v5, -v7, v5, v4
	v_cmp_lt_f32_e64 s[4:5], 0, v5
	s_nop 1
	v_cndmask_b32_e64 v5, v6, v7, s[4:5]
	v_mul_f32_e32 v6, 0x37800000, v5
	v_cndmask_b32_e32 v5, v5, v6, vcc
	v_cmp_class_f32_e32 vcc, v4, v226
	s_nop 1
	v_cndmask_b32_e32 v4, v5, v4, vcc
	v_div_scale_f32 v5, s[0:1], v4, v4, 1.0
	v_rcp_f32_e32 v6, v5
	s_nop 0
	v_fma_f32 v7, -v5, v6, 1.0
	v_fmac_f32_e32 v6, v7, v6
	v_div_scale_f32 v7, vcc, 1.0, v4, 1.0
	v_mul_f32_e32 v8, v7, v6
	v_fma_f32 v9, -v5, v8, v7
	v_fmac_f32_e32 v8, v9, v6
	v_fma_f32 v5, -v5, v8, v7
	v_div_fmas_f32 v5, v5, v6, v8
	v_div_fixup_f32 v4, v5, v4, 1.0
	ds_write_b32 v3, v4 offset:4096
	v_mov_b32_e32 v4, v100
	v_fmamk_f32 v4, v4, 0x3a000000, v225
	v_mul_f32_e32 v5, 0x4f800000, v4
	v_cmp_gt_f32_e32 vcc, s14, v4
	s_nop 1
	v_cndmask_b32_e32 v4, v4, v5, vcc
	v_sqrt_f32_e32 v5, v4
	s_nop 0
	v_add_u32_e32 v6, -1, v5
	v_fma_f32 v7, -v6, v5, v4
	v_cmp_ge_f32_e64 s[4:5], 0, v7
	v_add_u32_e32 v7, 1, v5
	s_nop 0
	v_cndmask_b32_e64 v6, v5, v6, s[4:5]
	v_fma_f32 v5, -v7, v5, v4
	v_cmp_lt_f32_e64 s[4:5], 0, v5
	s_nop 1
	v_cndmask_b32_e64 v5, v6, v7, s[4:5]
	v_mul_f32_e32 v6, 0x37800000, v5
	v_cndmask_b32_e32 v5, v5, v6, vcc
	v_cmp_class_f32_e32 vcc, v4, v226
	s_nop 1
	v_cndmask_b32_e32 v4, v5, v4, vcc
	v_div_scale_f32 v5, s[0:1], v4, v4, 1.0
	v_rcp_f32_e32 v6, v5
	s_nop 0
	v_fma_f32 v7, -v5, v6, 1.0
	v_fmac_f32_e32 v6, v7, v6
	v_div_scale_f32 v7, vcc, 1.0, v4, 1.0
	v_mul_f32_e32 v8, v7, v6
	v_fma_f32 v9, -v5, v8, v7
	v_fmac_f32_e32 v8, v9, v6
	v_fma_f32 v5, -v5, v8, v7
	v_div_fmas_f32 v5, v5, v6, v8
	v_div_fixup_f32 v4, v5, v4, 1.0
	ds_write_b32 v3, v4 offset:6144

; #define GAS __attribute__((address_space(1)))
; #define SB() __builtin_amdgcn_sched_barrier(0)
; DI const LAS float* rstd_table(const Frame& F) {
;     ...
;     for (int r = F.tid; r < 2048; r += 512) { f32x4 p[8];
; #pragma unroll
;         for (int q = 0; q < 8; ++q) p[q] = ((const GAS f32x4*)(P + (size_t)r * 32))[q];
;         SB();
;         f32x4 t = (p[0] + p[1]) + (p[2] + p[3]) + ((p[4] + p[5]) + (p[6] + p[7]));
;         tab[r] = 1.f / sqrtf(((t[0] + t[1]) + (t[2] + t[3])) * (1.f / D) + NORM_EPS);
.LBB0_1379:
	v_mbcnt_lo_u32_b32 v139, -1, 0
	v_mbcnt_hi_u32_b32 v139, -1, v139
	v_and_b32_e32 v138, 7, v139
	v_mul_u32_u24_e32 v140, 0x70, v138
	v_sub_co_u32_e32 v0, vcc, v0, v140
	s_nop 1
	v_subbrev_co_u32_e32 v1, vcc, 0, v1, vcc
	v_lshl_add_u64 v[132:133], v[0:1], 0, s[14:15]
	v_lshl_add_u64 v[134:135], v[132:133], 0, s[14:15]
	v_lshl_add_u64 v[136:137], v[134:135], 0, s[14:15]
	global_load_dwordx4 v[4:7], v[0:1], off
	global_load_dwordx4 v[8:11], v[0:1], off offset:128
	global_load_dwordx4 v[12:15], v[0:1], off offset:256
	global_load_dwordx4 v[16:19], v[0:1], off offset:384
	global_load_dwordx4 v[20:23], v[0:1], off offset:512
	global_load_dwordx4 v[24:27], v[0:1], off offset:640
	global_load_dwordx4 v[28:31], v[0:1], off offset:768
	global_load_dwordx4 v[32:35], v[0:1], off offset:896
	global_load_dwordx4 v[36:39], v[132:133], off
	global_load_dwordx4 v[40:43], v[132:133], off offset:128
	global_load_dwordx4 v[44:47], v[132:133], off offset:256
	global_load_dwordx4 v[48:51], v[132:133], off offset:384
	global_load_dwordx4 v[52:55], v[132:133], off offset:512
	global_load_dwordx4 v[56:59], v[132:133], off offset:640
	global_load_dwordx4 v[60:63], v[132:133], off offset:768
	global_load_dwordx4 v[64:67], v[132:133], off offset:896
	global_load_dwordx4 v[68:71], v[134:135], off
	global_load_dwordx4 v[72:75], v[134:135], off offset:128
	global_load_dwordx4 v[76:79], v[134:135], off offset:256
	global_load_dwordx4 v[80:83], v[134:135], off offset:384
	global_load_dwordx4 v[84:87], v[134:135], off offset:512
	global_load_dwordx4 v[88:91], v[134:135], off offset:640
	global_load_dwordx4 v[92:95], v[134:135], off offset:768
	global_load_dwordx4 v[96:99], v[134:135], off offset:896
	global_load_dwordx4 v[100:103], v[136:137], off
	global_load_dwordx4 v[104:107], v[136:137], off offset:128
	global_load_dwordx4 v[108:111], v[136:137], off offset:256
	global_load_dwordx4 v[112:115], v[136:137], off offset:384
	global_load_dwordx4 v[116:119], v[136:137], off offset:512
	global_load_dwordx4 v[120:123], v[136:137], off offset:640
	global_load_dwordx4 v[124:127], v[136:137], off offset:768
	global_load_dwordx4 v[128:131], v[136:137], off offset:896
	s_waitcnt vmcnt(24)
	v_pk_add_f32 v[4:5], v[4:5], v[6:7]
	v_pk_add_f32 v[8:9], v[8:9], v[10:11]
	v_pk_add_f32 v[12:13], v[12:13], v[14:15]
	v_pk_add_f32 v[16:17], v[16:17], v[18:19]
	v_pk_add_f32 v[20:21], v[20:21], v[22:23]
	v_pk_add_f32 v[24:25], v[24:25], v[26:27]
	v_pk_add_f32 v[28:29], v[28:29], v[30:31]
	v_pk_add_f32 v[32:33], v[32:33], v[34:35]
	v_add_f32_e32 v4, v4, v5
	v_add_f32_e32 v8, v8, v9
	v_add_f32_e32 v12, v12, v13
	v_add_f32_e32 v16, v16, v17
	v_add_f32_e32 v20, v20, v21
	v_add_f32_e32 v24, v24, v25
	v_add_f32_e32 v28, v28, v29
	v_add_f32_e32 v32, v32, v33
	v_add_f32_dpp v4, v4, v4 quad_perm:[1,0,3,2] row_mask:0xf bank_mask:0xf
	v_add_f32_dpp v8, v8, v8 quad_perm:[1,0,3,2] row_mask:0xf bank_mask:0xf
	v_add_f32_dpp v12, v12, v12 quad_perm:[1,0,3,2] row_mask:0xf bank_mask:0xf
	v_add_f32_dpp v16, v16, v16 quad_perm:[1,0,3,2] row_mask:0xf bank_mask:0xf
	v_add_f32_dpp v20, v20, v20 quad_perm:[1,0,3,2] row_mask:0xf bank_mask:0xf
	v_add_f32_dpp v24, v24, v24 quad_perm:[1,0,3,2] row_mask:0xf bank_mask:0xf
	v_add_f32_dpp v28, v28, v28 quad_perm:[1,0,3,2] row_mask:0xf bank_mask:0xf
	v_add_f32_dpp v32, v32, v32 quad_perm:[1,0,3,2] row_mask:0xf bank_mask:0xf
	v_add_f32_dpp v4, v4, v4 quad_perm:[2,3,0,1] row_mask:0xf bank_mask:0xf
	v_add_f32_dpp v8, v8, v8 quad_perm:[2,3,0,1] row_mask:0xf bank_mask:0xf
	v_add_f32_dpp v12, v12, v12 quad_perm:[2,3,0,1] row_mask:0xf bank_mask:0xf
	v_add_f32_dpp v16, v16, v16 quad_perm:[2,3,0,1] row_mask:0xf bank_mask:0xf
	v_add_f32_dpp v20, v20, v20 quad_perm:[2,3,0,1] row_mask:0xf bank_mask:0xf
	v_add_f32_dpp v24, v24, v24 quad_perm:[2,3,0,1] row_mask:0xf bank_mask:0xf
	v_add_f32_dpp v28, v28, v28 quad_perm:[2,3,0,1] row_mask:0xf bank_mask:0xf
	v_add_f32_dpp v32, v32, v32 quad_perm:[2,3,0,1] row_mask:0xf bank_mask:0xf
	v_add_f32_dpp v4, v4, v4 row_half_mirror row_mask:0xf bank_mask:0xf
	v_add_f32_dpp v8, v8, v8 row_half_mirror row_mask:0xf bank_mask:0xf
	v_add_f32_dpp v12, v12, v12 row_half_mirror row_mask:0xf bank_mask:0xf
	v_add_f32_dpp v16, v16, v16 row_half_mirror row_mask:0xf bank_mask:0xf
	v_add_f32_dpp v20, v20, v20 row_half_mirror row_mask:0xf bank_mask:0xf
	v_add_f32_dpp v24, v24, v24 row_half_mirror row_mask:0xf bank_mask:0xf
	v_add_f32_dpp v28, v28, v28 row_half_mirror row_mask:0xf bank_mask:0xf
	v_add_f32_dpp v32, v32, v32 row_half_mirror row_mask:0xf bank_mask:0xf
	v_cmp_eq_u32_e32 vcc, 1, v138
	s_nop 1
	v_cndmask_b32_e32 v4, v4, v8, vcc
	v_cmp_eq_u32_e32 vcc, 2, v138
	s_nop 1
	v_cndmask_b32_e32 v4, v4, v12, vcc
	v_cmp_eq_u32_e32 vcc, 3, v138
	s_nop 1
	v_cndmask_b32_e32 v4, v4, v16, vcc
	v_cmp_eq_u32_e32 vcc, 4, v138
	s_nop 1
	v_cndmask_b32_e32 v4, v4, v20, vcc
	v_cmp_eq_u32_e32 vcc, 5, v138
	s_nop 1
	v_cndmask_b32_e32 v4, v4, v24, vcc
	v_cmp_eq_u32_e32 vcc, 6, v138
	s_nop 1
	v_cndmask_b32_e32 v4, v4, v28, vcc
	v_cmp_eq_u32_e32 vcc, 7, v138
	s_nop 1
	v_cndmask_b32_e32 v4, v4, v32, vcc
	s_waitcnt vmcnt(16)
; #define GAS __attribute__((address_space(1)))
; #define SB() __builtin_amdgcn_sched_barrier(0)
; DI const LAS float* rstd_table(const Frame& F) {
;     ...
;     for (int r = F.tid; r < 2048; r += 512) { f32x4 p[8];
; #pragma unroll
;         for (int q = 0; q < 8; ++q) p[q] = ((const GAS f32x4*)(P + (size_t)r * 32))[q];
;         SB();
;         f32x4 t = (p[0] + p[1]) + (p[2] + p[3]) + ((p[4] + p[5]) + (p[6] + p[7]));
;         tab[r] = 1.f / sqrtf(((t[0] + t[1]) + (t[2] + t[3])) * (1.f / D) + NORM_EPS);
	v_pk_add_f32 v[36:37], v[36:37], v[38:39]
	v_pk_add_f32 v[40:41], v[40:41], v[42:43]
	v_pk_add_f32 v[44:45], v[44:45], v[46:47]
	v_pk_add_f32 v[48:49], v[48:49], v[50:51]
	v_pk_add_f32 v[52:53], v[52:53], v[54:55]
	v_pk_add_f32 v[56:57], v[56:57], v[58:59]
	v_pk_add_f32 v[60:61], v[60:61], v[62:63]
	v_pk_add_f32 v[64:65], v[64:65], v[66:67]
	v_add_f32_e32 v36, v36, v37
	v_add_f32_e32 v40, v40, v41
	v_add_f32_e32 v44, v44, v45
	v_add_f32_e32 v48, v48, v49
	v_add_f32_e32 v52, v52, v53
	v_add_f32_e32 v56, v56, v57
	v_add_f32_e32 v60, v60, v61
	v_add_f32_e32 v64, v64, v65
	v_add_f32_dpp v36, v36, v36 quad_perm:[1,0,3,2] row_mask:0xf bank_mask:0xf
	v_add_f32_dpp v40, v40, v40 quad_perm:[1,0,3,2] row_mask:0xf bank_mask:0xf
	v_add_f32_dpp v44, v44, v44 quad_perm:[1,0,3,2] row_mask:0xf bank_mask:0xf
	v_add_f32_dpp v48, v48, v48 quad_perm:[1,0,3,2] row_mask:0xf bank_mask:0xf
	v_add_f32_dpp v52, v52, v52 quad_perm:[1,0,3,2] row_mask:0xf bank_mask:0xf
	v_add_f32_dpp v56, v56, v56 quad_perm:[1,0,3,2] row_mask:0xf bank_mask:0xf
	v_add_f32_dpp v60, v60, v60 quad_perm:[1,0,3,2] row_mask:0xf bank_mask:0xf
	v_add_f32_dpp v64, v64, v64 quad_perm:[1,0,3,2] row_mask:0xf bank_mask:0xf
	v_add_f32_dpp v36, v36, v36 quad_perm:[2,3,0,1] row_mask:0xf bank_mask:0xf
	v_add_f32_dpp v40, v40, v40 quad_perm:[2,3,0,1] row_mask:0xf bank_mask:0xf
	v_add_f32_dpp v44, v44, v44 quad_perm:[2,3,0,1] row_mask:0xf bank_mask:0xf
	v_add_f32_dpp v48, v48, v48 quad_perm:[2,3,0,1] row_mask:0xf bank_mask:0xf
	v_add_f32_dpp v52, v52, v52 quad_perm:[2,3,0,1] row_mask:0xf bank_mask:0xf
	v_add_f32_dpp v56, v56, v56 quad_perm:[2,3,0,1] row_mask:0xf bank_mask:0xf
	v_add_f32_dpp v60, v60, v60 quad_perm:[2,3,0,1] row_mask:0xf bank_mask:0xf
	v_add_f32_dpp v64, v64, v64 quad_perm:[2,3,0,1] row_mask:0xf bank_mask:0xf
	v_add_f32_dpp v36, v36, v36 row_half_mirror row_mask:0xf bank_mask:0xf
	v_add_f32_dpp v40, v40, v40 row_half_mirror row_mask:0xf bank_mask:0xf
	v_add_f32_dpp v44, v44, v44 row_half_mirror row_mask:0xf bank_mask:0xf
	v_add_f32_dpp v48, v48, v48 row_half_mirror row_mask:0xf bank_mask:0xf
	v_add_f32_dpp v52, v52, v52 row_half_mirror row_mask:0xf bank_mask:0xf
	v_add_f32_dpp v56, v56, v56 row_half_mirror row_mask:0xf bank_mask:0xf
	v_add_f32_dpp v60, v60, v60 row_half_mirror row_mask:0xf bank_mask:0xf
	v_add_f32_dpp v64, v64, v64 row_half_mirror row_mask:0xf bank_mask:0xf
	v_cmp_eq_u32_e32 vcc, 1, v138
	s_nop 1
	v_cndmask_b32_e32 v36, v36, v40, vcc
	v_cmp_eq_u32_e32 vcc, 2, v138
	s_nop 1
	v_cndmask_b32_e32 v36, v36, v44, vcc
	v_cmp_eq_u32_e32 vcc, 3, v138
	s_nop 1
	v_cndmask_b32_e32 v36, v36, v48, vcc
	v_cmp_eq_u32_e32 vcc, 4, v138
	s_nop 1
	v_cndmask_b32_e32 v36, v36, v52, vcc
	v_cmp_eq_u32_e32 vcc, 5, v138
	s_nop 1
	v_cndmask_b32_e32 v36, v36, v56, vcc
	v_cmp_eq_u32_e32 vcc, 6, v138
	s_nop 1
	v_cndmask_b32_e32 v36, v36, v60, vcc
	v_cmp_eq_u32_e32 vcc, 7, v138
	s_nop 1
	v_cndmask_b32_e32 v36, v36, v64, vcc
	s_waitcnt vmcnt(8)
	v_pk_add_f32 v[68:69], v[68:69], v[70:71]
	v_pk_add_f32 v[72:73], v[72:73], v[74:75]
	v_pk_add_f32 v[76:77], v[76:77], v[78:79]
	v_pk_add_f32 v[80:81], v[80:81], v[82:83]
	v_pk_add_f32 v[84:85], v[84:85], v[86:87]
	v_pk_add_f32 v[88:89], v[88:89], v[90:91]
	v_pk_add_f32 v[92:93], v[92:93], v[94:95]
	v_pk_add_f32 v[96:97], v[96:97], v[98:99]
	v_add_f32_e32 v68, v68, v69
	v_add_f32_e32 v72, v72, v73
	v_add_f32_e32 v76, v76, v77
	v_add_f32_e32 v80, v80, v81
	v_add_f32_e32 v84, v84, v85
	v_add_f32_e32 v88, v88, v89
	v_add_f32_e32 v92, v92, v93
	v_add_f32_e32 v96, v96, v97
	v_add_f32_dpp v68, v68, v68 quad_perm:[1,0,3,2] row_mask:0xf bank_mask:0xf
	v_add_f32_dpp v72, v72, v72 quad_perm:[1,0,3,2] row_mask:0xf bank_mask:0xf
	v_add_f32_dpp v76, v76, v76 quad_perm:[1,0,3,2] row_mask:0xf bank_mask:0xf
	v_add_f32_dpp v80, v80, v80 quad_perm:[1,0,3,2] row_mask:0xf bank_mask:0xf
	v_add_f32_dpp v84, v84, v84 quad_perm:[1,0,3,2] row_mask:0xf bank_mask:0xf
	v_add_f32_dpp v88, v88, v88 quad_perm:[1,0,3,2] row_mask:0xf bank_mask:0xf
	v_add_f32_dpp v92, v92, v92 quad_perm:[1,0,3,2] row_mask:0xf bank_mask:0xf
	v_add_f32_dpp v96, v96, v96 quad_perm:[1,0,3,2] row_mask:0xf bank_mask:0xf
	v_add_f32_dpp v68, v68, v68 quad_perm:[2,3,0,1] row_mask:0xf bank_mask:0xf
	v_add_f32_dpp v72, v72, v72 quad_perm:[2,3,0,1] row_mask:0xf bank_mask:0xf
	v_add_f32_dpp v76, v76, v76 quad_perm:[2,3,0,1] row_mask:0xf bank_mask:0xf
	v_add_f32_dpp v80, v80, v80 quad_perm:[2,3,0,1] row_mask:0xf bank_mask:0xf
	v_add_f32_dpp v84, v84, v84 quad_perm:[2,3,0,1] row_mask:0xf bank_mask:0xf
	v_add_f32_dpp v88, v88, v88 quad_perm:[2,3,0,1] row_mask:0xf bank_mask:0xf
	v_add_f32_dpp v92, v92, v92 quad_perm:[2,3,0,1] row_mask:0xf bank_mask:0xf
	v_add_f32_dpp v96, v96, v96 quad_perm:[2,3,0,1] row_mask:0xf bank_mask:0xf
	v_add_f32_dpp v68, v68, v68 row_half_mirror row_mask:0xf bank_mask:0xf
	v_add_f32_dpp v72, v72, v72 row_half_mirror row_mask:0xf bank_mask:0xf
	v_add_f32_dpp v76, v76, v76 row_half_mirror row_mask:0xf bank_mask:0xf
	v_add_f32_dpp v80, v80, v80 row_half_mirror row_mask:0xf bank_mask:0xf
	v_add_f32_dpp v84, v84, v84 row_half_mirror row_mask:0xf bank_mask:0xf
	v_add_f32_dpp v88, v88, v88 row_half_mirror row_mask:0xf bank_mask:0xf
	v_add_f32_dpp v92, v92, v92 row_half_mirror row_mask:0xf bank_mask:0xf
	v_add_f32_dpp v96, v96, v96 row_half_mirror row_mask:0xf bank_mask:0xf
	v_cmp_eq_u32_e32 vcc, 1, v138
	s_nop 1
	v_cndmask_b32_e32 v68, v68, v72, vcc
	v_cmp_eq_u32_e32 vcc, 2, v138
	s_nop 1
	v_cndmask_b32_e32 v68, v68, v76, vcc
	v_cmp_eq_u32_e32 vcc, 3, v138
	s_nop 1
	v_cndmask_b32_e32 v68, v68, v80, vcc
	v_cmp_eq_u32_e32 vcc, 4, v138
	s_nop 1
	v_cndmask_b32_e32 v68, v68, v84, vcc
	v_cmp_eq_u32_e32 vcc, 5, v138
	s_nop 1
	v_cndmask_b32_e32 v68, v68, v88, vcc
	v_cmp_eq_u32_e32 vcc, 6, v138
	s_nop 1
	v_cndmask_b32_e32 v68, v68, v92, vcc
	v_cmp_eq_u32_e32 vcc, 7, v138
	s_nop 1
	v_cndmask_b32_e32 v68, v68, v96, vcc
	s_waitcnt vmcnt(0)
; #define GAS __attribute__((address_space(1)))
; #define SB() __builtin_amdgcn_sched_barrier(0)
; DI const LAS float* rstd_table(const Frame& F) {
;     ...
;     for (int r = F.tid; r < 2048; r += 512) { f32x4 p[8];
; #pragma unroll
;         for (int q = 0; q < 8; ++q) p[q] = ((const GAS f32x4*)(P + (size_t)r * 32))[q];
;         SB();
;         f32x4 t = (p[0] + p[1]) + (p[2] + p[3]) + ((p[4] + p[5]) + (p[6] + p[7]));
;         tab[r] = 1.f / sqrtf(((t[0] + t[1]) + (t[2] + t[3])) * (1.f / D) + NORM_EPS);
	v_pk_add_f32 v[100:101], v[100:101], v[102:103]
	v_pk_add_f32 v[104:105], v[104:105], v[106:107]
	v_pk_add_f32 v[108:109], v[108:109], v[110:111]
	v_pk_add_f32 v[112:113], v[112:113], v[114:115]
	v_pk_add_f32 v[116:117], v[116:117], v[118:119]
	v_pk_add_f32 v[120:121], v[120:121], v[122:123]
	v_pk_add_f32 v[124:125], v[124:125], v[126:127]
	v_pk_add_f32 v[128:129], v[128:129], v[130:131]
	v_add_f32_e32 v100, v100, v101
	v_add_f32_e32 v104, v104, v105
	v_add_f32_e32 v108, v108, v109
	v_add_f32_e32 v112, v112, v113
	v_add_f32_e32 v116, v116, v117
	v_add_f32_e32 v120, v120, v121
	v_add_f32_e32 v124, v124, v125
	v_add_f32_e32 v128, v128, v129
	v_add_f32_dpp v100, v100, v100 quad_perm:[1,0,3,2] row_mask:0xf bank_mask:0xf
	v_add_f32_dpp v104, v104, v104 quad_perm:[1,0,3,2] row_mask:0xf bank_mask:0xf
	v_add_f32_dpp v108, v108, v108 quad_perm:[1,0,3,2] row_mask:0xf bank_mask:0xf
	v_add_f32_dpp v112, v112, v112 quad_perm:[1,0,3,2] row_mask:0xf bank_mask:0xf
	v_add_f32_dpp v116, v116, v116 quad_perm:[1,0,3,2] row_mask:0xf bank_mask:0xf
	v_add_f32_dpp v120, v120, v120 quad_perm:[1,0,3,2] row_mask:0xf bank_mask:0xf
	v_add_f32_dpp v124, v124, v124 quad_perm:[1,0,3,2] row_mask:0xf bank_mask:0xf
	v_add_f32_dpp v128, v128, v128 quad_perm:[1,0,3,2] row_mask:0xf bank_mask:0xf
	v_add_f32_dpp v100, v100, v100 quad_perm:[2,3,0,1] row_mask:0xf bank_mask:0xf
	v_add_f32_dpp v104, v104, v104 quad_perm:[2,3,0,1] row_mask:0xf bank_mask:0xf
	v_add_f32_dpp v108, v108, v108 quad_perm:[2,3,0,1] row_mask:0xf bank_mask:0xf
	v_add_f32_dpp v112, v112, v112 quad_perm:[2,3,0,1] row_mask:0xf bank_mask:0xf
	v_add_f32_dpp v116, v116, v116 quad_perm:[2,3,0,1] row_mask:0xf bank_mask:0xf
	v_add_f32_dpp v120, v120, v120 quad_perm:[2,3,0,1] row_mask:0xf bank_mask:0xf
	v_add_f32_dpp v124, v124, v124 quad_perm:[2,3,0,1] row_mask:0xf bank_mask:0xf
	v_add_f32_dpp v128, v128, v128 quad_perm:[2,3,0,1] row_mask:0xf bank_mask:0xf
	v_add_f32_dpp v100, v100, v100 row_half_mirror row_mask:0xf bank_mask:0xf
	v_add_f32_dpp v104, v104, v104 row_half_mirror row_mask:0xf bank_mask:0xf
	v_add_f32_dpp v108, v108, v108 row_half_mirror row_mask:0xf bank_mask:0xf
	v_add_f32_dpp v112, v112, v112 row_half_mirror row_mask:0xf bank_mask:0xf
	v_add_f32_dpp v116, v116, v116 row_half_mirror row_mask:0xf bank_mask:0xf
	v_add_f32_dpp v120, v120, v120 row_half_mirror row_mask:0xf bank_mask:0xf
	v_add_f32_dpp v124, v124, v124 row_half_mirror row_mask:0xf bank_mask:0xf
	v_add_f32_dpp v128, v128, v128 row_half_mirror row_mask:0xf bank_mask:0xf
	v_cmp_eq_u32_e32 vcc, 1, v138
	s_nop 1
	v_cndmask_b32_e32 v100, v100, v104, vcc
	v_cmp_eq_u32_e32 vcc, 2, v138
	s_nop 1
	v_cndmask_b32_e32 v100, v100, v108, vcc
	v_cmp_eq_u32_e32 vcc, 3, v138
	s_nop 1
	v_cndmask_b32_e32 v100, v100, v112, vcc
	v_cmp_eq_u32_e32 vcc, 4, v138
	s_nop 1
	v_cndmask_b32_e32 v100, v100, v116, vcc
	v_cmp_eq_u32_e32 vcc, 5, v138
	s_nop 1
	v_cndmask_b32_e32 v100, v100, v120, vcc
	v_cmp_eq_u32_e32 vcc, 6, v138
	s_nop 1
	v_cndmask_b32_e32 v100, v100, v124, vcc
	v_cmp_eq_u32_e32 vcc, 7, v138
	s_nop 1
	v_cndmask_b32_e32 v100, v100, v128, vcc
	v_fmamk_f32 v4, v4, 0x3a000000, v225
	v_mul_f32_e32 v5, 0x4f800000, v4
	v_cmp_gt_f32_e32 vcc, s43, v4
	s_nop 1
	v_cndmask_b32_e32 v4, v4, v5, vcc
	v_sqrt_f32_e32 v5, v4
	s_nop 0
	v_add_u32_e32 v6, -1, v5
	v_fma_f32 v7, -v6, v5, v4
	v_cmp_ge_f32_e64 s[4:5], 0, v7
	v_add_u32_e32 v7, 1, v5
	s_nop 0
	v_cndmask_b32_e64 v6, v5, v6, s[4:5]
	v_fma_f32 v5, -v7, v5, v4
	v_cmp_lt_f32_e64 s[4:5], 0, v5
	s_nop 1
	v_cndmask_b32_e64 v5, v6, v7, s[4:5]
	v_mul_f32_e32 v6, 0x37800000, v5
	v_cndmask_b32_e32 v5, v5, v6, vcc
	v_cmp_class_f32_e32 vcc, v4, v226
	s_nop 1
	v_cndmask_b32_e32 v4, v5, v4, vcc
	v_div_scale_f32 v5, s[0:1], v4, v4, 1.0
	v_rcp_f32_e32 v6, v5
	s_nop 0
	v_fma_f32 v7, -v5, v6, 1.0
	v_fmac_f32_e32 v6, v7, v6
	v_div_scale_f32 v7, vcc, 1.0, v4, 1.0
	v_mul_f32_e32 v8, v7, v6
	v_fma_f32 v9, -v5, v8, v7
	v_fmac_f32_e32 v8, v9, v6
	v_fma_f32 v5, -v5, v8, v7
	v_div_fmas_f32 v5, v5, v6, v8
	v_div_fixup_f32 v4, v5, v4, 1.0
	ds_write_b32 v3, v4
	v_mov_b32_e32 v4, v36
	v_fmamk_f32 v4, v4, 0x3a000000, v225
	v_mul_f32_e32 v5, 0x4f800000, v4
	v_cmp_gt_f32_e32 vcc, s43, v4
	s_nop 1
	v_cndmask_b32_e32 v4, v4, v5, vcc
	v_sqrt_f32_e32 v5, v4
	s_nop 0
	v_add_u32_e32 v6, -1, v5
	v_fma_f32 v7, -v6, v5, v4
	v_cmp_ge_f32_e64 s[4:5], 0, v7
	v_add_u32_e32 v7, 1, v5
	s_nop 0
	v_cndmask_b32_e64 v6, v5, v6, s[4:5]
	v_fma_f32 v5, -v7, v5, v4
	v_cmp_lt_f32_e64 s[4:5], 0, v5
	s_nop 1
	v_cndmask_b32_e64 v5, v6, v7, s[4:5]
	v_mul_f32_e32 v6, 0x37800000, v5
	v_cndmask_b32_e32 v5, v5, v6, vcc
	v_cmp_class_f32_e32 vcc, v4, v226
	s_nop 1
	v_cndmask_b32_e32 v4, v5, v4, vcc
	v_div_scale_f32 v5, s[0:1], v4, v4, 1.0
	v_rcp_f32_e32 v6, v5
	s_nop 0
	v_fma_f32 v7, -v5, v6, 1.0
	v_fmac_f32_e32 v6, v7, v6
	v_div_scale_f32 v7, vcc, 1.0, v4, 1.0
	v_mul_f32_e32 v8, v7, v6
	v_fma_f32 v9, -v5, v8, v7
	v_fmac_f32_e32 v8, v9, v6
	v_fma_f32 v5, -v5, v8, v7
	v_div_fmas_f32 v5, v5, v6, v8
	v_div_fixup_f32 v4, v5, v4, 1.0
	ds_write_b32 v3, v4 offset:2048
	v_mov_b32_e32 v4, v68
	v_fmamk_f32 v4, v4, 0x3a000000, v225
	v_mul_f32_e32 v5, 0x4f800000, v4
	v_cmp_gt_f32_e32 vcc, s43, v4
	s_nop 1
	v_cndmask_b32_e32 v4, v4, v5, vcc
	v_sqrt_f32_e32 v5, v4
	s_nop 0
	v_add_u32_e32 v6, -1, v5
	v_fma_f32 v7, -v6, v5, v4
	v_cmp_ge_f32_e64 s[4:5], 0, v7
	v_add_u32_e32 v7, 1, v5
	s_nop 0
	v_cndmask_b32_e64 v6, v5, v6, s[4:5]
	v_fma_f32 v5, -v7, v5, v4
	v_cmp_lt_f32_e64 s[4:5], 0, v5
	s_nop 1
	v_cndmask_b32_e64 v5, v6, v7, s[4:5]
	v_mul_f32_e32 v6, 0x37800000, v5
	v_cndmask_b32_e32 v5, v5, v6, vcc
	v_cmp_class_f32_e32 vcc, v4, v226
	s_nop 1
	v_cndmask_b32_e32 v4, v5, v4, vcc
	v_div_scale_f32 v5, s[0:1], v4, v4, 1.0
	v_rcp_f32_e32 v6, v5
	s_nop 0
	v_fma_f32 v7, -v5, v6, 1.0
	v_fmac_f32_e32 v6, v7, v6
	v_div_scale_f32 v7, vcc, 1.0, v4, 1.0
	v_mul_f32_e32 v8, v7, v6
	v_fma_f32 v9, -v5, v8, v7
	v_fmac_f32_e32 v8, v9, v6
	v_fma_f32 v5, -v5, v8, v7
	v_div_fmas_f32 v5, v5, v6, v8
	v_div_fixup_f32 v4, v5, v4, 1.0
	ds_write_b32 v3, v4 offset:4096
	v_mov_b32_e32 v4, v100
	v_fmamk_f32 v4, v4, 0x3a000000, v225
	v_mul_f32_e32 v5, 0x4f800000, v4
	v_cmp_gt_f32_e32 vcc, s43, v4
	s_nop 1
	v_cndmask_b32_e32 v4, v4, v5, vcc
	v_sqrt_f32_e32 v5, v4
	s_nop 0
	v_add_u32_e32 v6, -1, v5
	v_fma_f32 v7, -v6, v5, v4
	v_cmp_ge_f32_e64 s[4:5], 0, v7
	v_add_u32_e32 v7, 1, v5
	s_nop 0
	v_cndmask_b32_e64 v6, v5, v6, s[4:5]
	v_fma_f32 v5, -v7, v5, v4
	v_cmp_lt_f32_e64 s[4:5], 0, v5
	s_nop 1
	v_cndmask_b32_e64 v5, v6, v7, s[4:5]
	v_mul_f32_e32 v6, 0x37800000, v5
	v_cndmask_b32_e32 v5, v5, v6, vcc
	v_cmp_class_f32_e32 vcc, v4, v226
	s_nop 1
	v_cndmask_b32_e32 v4, v5, v4, vcc
	v_div_scale_f32 v5, s[0:1], v4, v4, 1.0
	v_rcp_f32_e32 v6, v5
	s_nop 0
	v_fma_f32 v7, -v5, v6, 1.0
	v_fmac_f32_e32 v6, v7, v6
	v_div_scale_f32 v7, vcc, 1.0, v4, 1.0
	v_mul_f32_e32 v8, v7, v6
	v_fma_f32 v9, -v5, v8, v7
	v_fmac_f32_e32 v8, v9, v6
	v_fma_f32 v5, -v5, v8, v7
	v_div_fmas_f32 v5, v5, v6, v8
	v_div_fixup_f32 v4, v5, v4, 1.0
	ds_write_b32 v3, v4 offset:6144
